# stick-breaking attention: f32 K/V base pointers formed once per item instead of per key block (no scalar load + wait inside the loop)
# baseline (speedup 1.0000x reference)
.LBB0_869:
	s_or_b64 exec, exec, s[52:53]
	s_add_u32 s46, s50, s46
	s_addc_u32 s47, s51, s47
	s_lshl_b64 s[44:45], s[44:45], 1
	s_add_u32 s44, s46, s44
	s_addc_u32 s45, s47, s45
	s_lshl_b64 s[22:23], s[22:23], 1
	s_add_u32 s22, s44, s22
	s_addc_u32 s23, s45, s23
	s_add_i32 s44, s60, s61
	s_add_i32 s45, s44, -2
	s_lshr_b32 s45, s45, 6
	s_cmp_gt_i32 s44, 1
	s_cselect_b32 s46, s45, 0
	s_lshl_b32 s60, s46, 6
	s_cmp_lg_u32 s40, 0x40f
	s_cbranch_scc1 .Lsb_pro_p
	s_sub_u32 s100, s94, 0xf0
	s_subb_u32 s101, s95, 0
	s_load_dwordx4 s[96:99], s[100:101], 0x0
	s_and_b32 s100, s57, 0xff
	s_mulk_i32 s100, 0xab
	s_lshr_b32 s100, s100, 11
	s_mul_i32 s100, s100, 0x600000
	s_lshl_b32 s101, s58, 9
	s_add_u32 s100, s100, s101
	s_waitcnt lgkmcnt(0)
	s_branch .Lsb_pro_j

.Lsb_pro_j:
	s_add_u32 s96, s96, s100
	s_addc_u32 s97, s97, 0
	s_add_u32 s98, s98, s100
	s_addc_u32 s99, s99, 0
	s_mov_b32 s101, 0
	s_cmp_eq_u32 s40, 0x40f
	s_cbranch_scc1 .Lsb_pro_bf16
	v_lshl_add_u64 v[74:75], s[18:19], 0, v[68:69]
	v_lshl_add_u64 v[76:77], s[22:23], 0, v[68:69]
	v_add_u32_e32 v192, s60, v234
	v_mul_u32_u24_e32 v192, 0x1800, v192
	v_lshl_add_u32 v192, v68, 1, v192
	v_add_u32_e32 v193, 0x30000, v192
	global_load_dwordx4 v[160:163], v192, s[96:97]
	global_load_dwordx4 v[164:167], v192, s[96:97] offset:16
	global_load_dwordx4 v[168:171], v192, s[98:99]
	global_load_dwordx4 v[172:175], v192, s[98:99] offset:16
	global_load_dwordx4 v[176:179], v193, s[96:97]
	global_load_dwordx4 v[180:183], v193, s[96:97] offset:16
	global_load_dwordx4 v[184:187], v193, s[98:99]
	global_load_dwordx4 v[188:191], v193, s[98:99] offset:16
	s_mov_b32 s101, 1
	s_branch .Lsb_pro_done

.Lsb_nocvt:
	s_waitcnt vmcnt(2)
	ds_write_b128 v64, v[48:51]
	v_add_u32_e32 v64, v88, v80
	ds_write_b128 v64, v[52:55] offset:17408
	v_add_u32_e32 v64, v88, v82
	v_cmp_gt_i32_e32 vcc, 1, v98
	s_waitcnt vmcnt(1)
	ds_write_b128 v64, v[56:59]
	v_add_u32_e32 v64, v88, v81
	s_and_b64 vcc, exec, vcc
	s_waitcnt vmcnt(0)
	ds_write_b128 v64, v[60:63] offset:17408
	s_waitcnt lgkmcnt(0)
	s_barrier
	s_cbranch_vccnz .LBB0_873
	v_add_u32_e32 v192, s60, v92
	v_mul_u32_u24_e32 v192, 0x1800, v192
	v_lshl_add_u32 v192, v68, 1, v192
	v_add_u32_e32 v193, 0x30000, v192
	global_load_dwordx4 v[160:163], v192, s[96:97]
	global_load_dwordx4 v[164:167], v192, s[96:97] offset:16
	global_load_dwordx4 v[168:171], v192, s[98:99]
	global_load_dwordx4 v[172:175], v192, s[98:99] offset:16
	global_load_dwordx4 v[176:179], v193, s[96:97]
	global_load_dwordx4 v[180:183], v193, s[96:97] offset:16
	global_load_dwordx4 v[184:187], v193, s[98:99]
	global_load_dwordx4 v[188:191], v193, s[98:99] offset:16
	s_mov_b32 s101, 1
	s_branch .LBB0_873
	v_add_u32_e32 v48, s60, v92
	v_add_u32_e32 v56, s60, v91
	v_min_i32_e32 v52, s40, v48
	v_min_i32_e32 v60, s40, v56
	v_mad_u64_u32 v[48:49], s[18:19], v52, s35, v[74:75]
	v_mad_u64_u32 v[52:53], s[18:19], v52, s35, v[76:77]
	v_mad_u64_u32 v[56:57], s[18:19], v60, s35, v[74:75]
	v_mad_u64_u32 v[60:61], s[18:19], v60, s35, v[76:77]
	global_load_dwordx4 v[48:51], v[48:49], off
	s_nop 0
	global_load_dwordx4 v[52:55], v[52:53], off
	s_nop 0
	global_load_dwordx4 v[56:59], v[56:57], off
	s_nop 0
	global_load_dwordx4 v[60:63], v[60:61], off
